# v8 plus accumulator zeroing with 64 v_mov_b64 instead of 128 v_mov_b32, SSD path-exact vmcnt and batched state-update LDS reads, no store drain at the attention unit barrier
# baseline (speedup 1.0000x reference)
; template <class Epi, class Sched, bool ALIGN_EPI = false, bool SP2 = false>
; __device__ __forceinline__ void gemm_phase(PG8_LAS unsigned char* lds, const Gemm g, const Sched& S, const Epi& E) {
;     ...
;         const bool has_next = S.next(ui + 1, nxt);
;         const char* nA = has_next ? (const char*)g.A + (size_t)nxt.pm * tstep + (size_t)nxt.kt0 * kstep : cA; const char* nB = has_next ? (const char*)g.Bt + (size_t)nxt.pn * tstep + (size_t)nxt.kt0 * kstep : cB;
;     ...
; #pragma unroll
;         for (int a = 0; a < 2; ++a)
; #pragma unroll
;             for (int b = 0; b < 2; ++b)
; #pragma unroll
;                 for (int m = 0; m < 4; ++m)
; #pragma unroll
;                     for (int n = 0; n < 2; ++n) acc[a][b][m][n] = (f32x4){0.f, 0.f, 0.f, 0.f};
.LBB0_815:
	s_ashr_i32 s45, s44, 31
	s_lshl_b64 s[26:27], s[44:45], 21
	s_add_u32 s43, s4, s26
	s_addc_u32 s45, s5, s27
	s_and_b64 s[26:27], s[38:39], exec
	s_cselect_b32 s47, s45, s51
	s_cselect_b32 s46, s43, s50
	s_ashr_i32 s43, s42, 31
	s_lshl_b64 s[26:27], s[42:43], 21
	s_add_u32 s43, s6, s26
	s_addc_u32 s45, s7, s27
	s_and_b64 s[26:27], s[38:39], exec
	s_cselect_b32 s49, s45, s1
	s_cselect_b32 s48, s43, s0
	s_add_u32 s50, s50, 0x100080
	s_addc_u32 s51, s51, 0
	s_add_u32 s43, s0, 0x100
	v_mov_b64_e32 v[4:5], 0
	s_addc_u32 s45, s1, 0
	s_mov_b32 s60, -2
	v_mov_b64_e32 v[6:7], 0
	v_mov_b64_e32 v[8:9], 0
	v_mov_b64_e32 v[10:11], 0
	v_mov_b64_e32 v[20:21], 0
	v_mov_b64_e32 v[22:23], 0
	v_mov_b64_e32 v[24:25], 0
	v_mov_b64_e32 v[26:27], 0
	v_mov_b64_e32 v[32:33], 0
	v_mov_b64_e32 v[34:35], 0
	v_mov_b64_e32 v[40:41], 0
	v_mov_b64_e32 v[42:43], 0
	v_mov_b64_e32 v[48:49], 0
	v_mov_b64_e32 v[50:51], 0
	v_mov_b64_e32 v[56:57], 0
	v_mov_b64_e32 v[58:59], 0
	v_mov_b64_e32 v[12:13], 0
	v_mov_b64_e32 v[14:15], 0
	v_mov_b64_e32 v[16:17], 0
	v_mov_b64_e32 v[18:19], 0
	v_mov_b64_e32 v[28:29], 0
	v_mov_b64_e32 v[30:31], 0
	v_mov_b64_e32 v[36:37], 0
	v_mov_b64_e32 v[38:39], 0
	v_mov_b64_e32 v[44:45], 0
	v_mov_b64_e32 v[46:47], 0
	v_mov_b64_e32 v[52:53], 0
	v_mov_b64_e32 v[54:55], 0
	v_mov_b64_e32 v[60:61], 0
	v_mov_b64_e32 v[62:63], 0
	v_mov_b64_e32 v[64:65], 0
	v_mov_b64_e32 v[66:67], 0
	v_mov_b64_e32 v[68:69], 0
	v_mov_b64_e32 v[70:71], 0
	v_mov_b64_e32 v[72:73], 0
	v_mov_b64_e32 v[74:75], 0
	v_mov_b64_e32 v[80:81], 0
	v_mov_b64_e32 v[82:83], 0
	v_mov_b64_e32 v[88:89], 0
	v_mov_b64_e32 v[90:91], 0
	v_mov_b64_e32 v[96:97], 0
	v_mov_b64_e32 v[98:99], 0
	v_mov_b64_e32 v[104:105], 0
	v_mov_b64_e32 v[106:107], 0
	v_mov_b64_e32 v[112:113], 0
	v_mov_b64_e32 v[114:115], 0
	v_mov_b64_e32 v[120:121], 0
	v_mov_b64_e32 v[122:123], 0
	v_mov_b64_e32 v[76:77], 0
	v_mov_b64_e32 v[78:79], 0
	v_mov_b64_e32 v[84:85], 0
	v_mov_b64_e32 v[86:87], 0
	v_mov_b64_e32 v[92:93], 0
	v_mov_b64_e32 v[94:95], 0
	v_mov_b64_e32 v[100:101], 0
	v_mov_b64_e32 v[102:103], 0
	v_mov_b64_e32 v[108:109], 0
	v_mov_b64_e32 v[110:111], 0
	v_mov_b64_e32 v[116:117], 0
	v_mov_b64_e32 v[118:119], 0
	v_mov_b64_e32 v[124:125], 0
	v_mov_b64_e32 v[126:127], 0
	v_mov_b64_e32 v[128:129], 0
	v_mov_b64_e32 v[130:131], 0
	v_add_u32_e32 v198, 0x10000, v151

; template <class Epi, class Sched, bool ALIGN_EPI = false, bool SP2 = false>
; __device__ __forceinline__ void gemm_phase(PG8_LAS unsigned char* lds, const Gemm g, const Sched& S, const Epi& E) {
;     ...
;         const bool has_next = S.next(ui + 1, nxt);
;         const char* nA = has_next ? (const char*)g.A + (size_t)nxt.pm * tstep + (size_t)nxt.kt0 * kstep : cA; const char* nB = has_next ? (const char*)g.Bt + (size_t)nxt.pn * tstep + (size_t)nxt.kt0 * kstep : cB;
;     ...
; #pragma unroll
;         for (int a = 0; a < 2; ++a)
; #pragma unroll
;             for (int b = 0; b < 2; ++b)
; #pragma unroll
;                 for (int m = 0; m < 4; ++m)
; #pragma unroll
;                     for (int n = 0; n < 2; ++n) acc[a][b][m][n] = (f32x4){0.f, 0.f, 0.f, 0.f};
.LBB0_1031:
	s_ashr_i32 s45, s44, 31
	s_lshl_b64 s[26:27], s[44:45], 19
	s_add_u32 s43, s6, s26
	s_addc_u32 s45, s7, s27
	s_and_b64 s[26:27], s[38:39], exec
	s_cselect_b32 s47, s45, s1
	s_cselect_b32 s46, s43, s0
	s_ashr_i32 s43, s42, 31
	s_lshl_b64 s[26:27], s[42:43], 19
	s_add_u32 s43, s8, s26
	s_addc_u32 s45, s9, s27
	s_and_b64 s[26:27], s[38:39], exec
	s_cselect_b32 s49, s45, s53
	s_cselect_b32 s48, s43, s52
	s_add_u32 s50, s0, 0x40080
	s_addc_u32 s51, s1, 0
	s_add_u32 s43, s52, 0x100
	v_mov_b64_e32 v[4:5], 0
	s_addc_u32 s45, s53, 0
	s_mov_b32 s52, -2
	v_mov_b64_e32 v[6:7], 0
	v_mov_b64_e32 v[8:9], 0
	v_mov_b64_e32 v[10:11], 0
	v_mov_b64_e32 v[12:13], 0
	v_mov_b64_e32 v[14:15], 0
	v_mov_b64_e32 v[16:17], 0
	v_mov_b64_e32 v[18:19], 0
	v_mov_b64_e32 v[28:29], 0
	v_mov_b64_e32 v[30:31], 0
	v_mov_b64_e32 v[32:33], 0
	v_mov_b64_e32 v[34:35], 0
	v_mov_b64_e32 v[44:45], 0
	v_mov_b64_e32 v[46:47], 0
	v_mov_b64_e32 v[48:49], 0
	v_mov_b64_e32 v[50:51], 0
	v_mov_b64_e32 v[20:21], 0
	v_mov_b64_e32 v[22:23], 0
	v_mov_b64_e32 v[24:25], 0
	v_mov_b64_e32 v[26:27], 0
	v_mov_b64_e32 v[36:37], 0
	v_mov_b64_e32 v[38:39], 0
	v_mov_b64_e32 v[40:41], 0
	v_mov_b64_e32 v[42:43], 0
	v_mov_b64_e32 v[52:53], 0
	v_mov_b64_e32 v[54:55], 0
	v_mov_b64_e32 v[56:57], 0
	v_mov_b64_e32 v[58:59], 0
	v_mov_b64_e32 v[60:61], 0
	v_mov_b64_e32 v[62:63], 0
	v_mov_b64_e32 v[64:65], 0
	v_mov_b64_e32 v[66:67], 0
	v_mov_b64_e32 v[68:69], 0
	v_mov_b64_e32 v[70:71], 0
	v_mov_b64_e32 v[72:73], 0
	v_mov_b64_e32 v[74:75], 0
	v_mov_b64_e32 v[76:77], 0
	v_mov_b64_e32 v[78:79], 0
	v_mov_b64_e32 v[80:81], 0
	v_mov_b64_e32 v[82:83], 0
	v_mov_b64_e32 v[92:93], 0
	v_mov_b64_e32 v[94:95], 0
	v_mov_b64_e32 v[96:97], 0
	v_mov_b64_e32 v[98:99], 0
	v_mov_b64_e32 v[108:109], 0
	v_mov_b64_e32 v[110:111], 0
	v_mov_b64_e32 v[112:113], 0
	v_mov_b64_e32 v[114:115], 0
	v_mov_b64_e32 v[84:85], 0
	v_mov_b64_e32 v[86:87], 0
	v_mov_b64_e32 v[88:89], 0
	v_mov_b64_e32 v[90:91], 0
	v_mov_b64_e32 v[100:101], 0
	v_mov_b64_e32 v[102:103], 0
	v_mov_b64_e32 v[104:105], 0
	v_mov_b64_e32 v[106:107], 0
	v_mov_b64_e32 v[116:117], 0
	v_mov_b64_e32 v[118:119], 0
	v_mov_b64_e32 v[120:121], 0
	v_mov_b64_e32 v[122:123], 0
	v_mov_b64_e32 v[124:125], 0
	v_mov_b64_e32 v[126:127], 0
	v_mov_b64_e32 v[128:129], 0
	v_mov_b64_e32 v[130:131], 0
	v_add_u32_e32 v198, 0x10000, v143

; template <class Epi, class Sched, bool ALIGN_EPI = false, bool SP2 = false>
; __device__ __forceinline__ void gemm_phase(PG8_LAS unsigned char* lds, const Gemm g, const Sched& S, const Epi& E) {
;     ...
;         const bool has_next = S.next(ui + 1, nxt);
;         const char* nA = has_next ? (const char*)g.A + (size_t)nxt.pm * tstep + (size_t)nxt.kt0 * kstep : cA; const char* nB = has_next ? (const char*)g.Bt + (size_t)nxt.pn * tstep + (size_t)nxt.kt0 * kstep : cB;
;     ...
; #pragma unroll
;         for (int a = 0; a < 2; ++a)
; #pragma unroll
;             for (int b = 0; b < 2; ++b)
; #pragma unroll
;                 for (int m = 0; m < 4; ++m)
; #pragma unroll
;                     for (int n = 0; n < 2; ++n) acc[a][b][m][n] = (f32x4){0.f, 0.f, 0.f, 0.f};
.LBB0_1050:
	s_ashr_i32 s45, s44, 31
	s_lshl_b64 s[46:47], s[44:45], 18
	s_add_u32 s46, s5, s46
	s_addc_u32 s47, s6, s47
	s_and_b64 s[48:49], s[40:41], exec
	s_cselect_b32 s45, s47, s1
	s_cselect_b32 s58, s46, s0
	s_ashr_i32 s43, s42, 31
	s_lshl_b64 s[48:49], s[42:43], 18
	s_add_u32 s48, s7, s48
	s_addc_u32 s49, s8, s49
	s_and_b64 s[52:53], s[40:41], exec
	s_cselect_b32 s43, s49, s27
	s_cselect_b32 s59, s48, s26
	s_add_u32 s52, s0, 0x20080
	s_addc_u32 s53, s1, 0
	s_add_u32 s60, s26, 0x100
	v_mov_b64_e32 v[4:5], 0
	s_addc_u32 s61, s27, 0
	s_mov_b32 s62, -2
	v_mov_b64_e32 v[6:7], 0
	v_mov_b64_e32 v[8:9], 0
	v_mov_b64_e32 v[10:11], 0
	v_mov_b64_e32 v[20:21], 0
	v_mov_b64_e32 v[22:23], 0
	v_mov_b64_e32 v[24:25], 0
	v_mov_b64_e32 v[26:27], 0
	v_mov_b64_e32 v[36:37], 0
	v_mov_b64_e32 v[38:39], 0
	v_mov_b64_e32 v[40:41], 0
	v_mov_b64_e32 v[42:43], 0
	v_mov_b64_e32 v[52:53], 0
	v_mov_b64_e32 v[54:55], 0
	v_mov_b64_e32 v[56:57], 0
	v_mov_b64_e32 v[58:59], 0
	v_mov_b64_e32 v[12:13], 0
	v_mov_b64_e32 v[14:15], 0
	v_mov_b64_e32 v[16:17], 0
	v_mov_b64_e32 v[18:19], 0
	v_mov_b64_e32 v[28:29], 0
	v_mov_b64_e32 v[30:31], 0
	v_mov_b64_e32 v[32:33], 0
	v_mov_b64_e32 v[34:35], 0
	v_mov_b64_e32 v[44:45], 0
	v_mov_b64_e32 v[46:47], 0
	v_mov_b64_e32 v[48:49], 0
	v_mov_b64_e32 v[50:51], 0
	v_mov_b64_e32 v[60:61], 0
	v_mov_b64_e32 v[62:63], 0
	v_mov_b64_e32 v[64:65], 0
	v_mov_b64_e32 v[66:67], 0
	v_mov_b64_e32 v[68:69], 0
	v_mov_b64_e32 v[70:71], 0
	v_mov_b64_e32 v[72:73], 0
	v_mov_b64_e32 v[74:75], 0
	v_mov_b64_e32 v[92:93], 0
	v_mov_b64_e32 v[94:95], 0
	v_mov_b64_e32 v[96:97], 0
	v_mov_b64_e32 v[98:99], 0
	v_mov_b64_e32 v[108:109], 0
	v_mov_b64_e32 v[110:111], 0
	v_mov_b64_e32 v[112:113], 0
	v_mov_b64_e32 v[114:115], 0
	v_mov_b64_e32 v[116:117], 0
	v_mov_b64_e32 v[118:119], 0
	v_mov_b64_e32 v[124:125], 0
	v_mov_b64_e32 v[126:127], 0
	v_mov_b64_e32 v[76:77], 0
	v_mov_b64_e32 v[78:79], 0
	v_mov_b64_e32 v[80:81], 0
	v_mov_b64_e32 v[82:83], 0
	v_mov_b64_e32 v[100:101], 0
	v_mov_b64_e32 v[102:103], 0
	v_mov_b64_e32 v[104:105], 0
	v_mov_b64_e32 v[106:107], 0
	v_mov_b64_e32 v[120:121], 0
	v_mov_b64_e32 v[122:123], 0
	v_mov_b64_e32 v[128:129], 0
	v_mov_b64_e32 v[130:131], 0
	v_mov_b64_e32 v[132:133], 0
	v_mov_b64_e32 v[134:135], 0
	v_mov_b64_e32 v[136:137], 0
	v_mov_b64_e32 v[138:139], 0
	v_add_u32_e32 v154, 0x10000, v157

; #define LAS __attribute__((address_space(3)))
; __device__ __forceinline__ unsigned pkbf(float lo, float hi) { f32x2v v = {lo, hi}; bf16x2v b = __builtin_convertvector(v, bf16x2v); return __builtin_bit_cast(unsigned, b); }
; DI float bf_lo(unsigned w) { return __uint_as_float(w << 16); }
; DI float bf_hi(unsigned w) { return __uint_as_float(w & 0xffff0000u); }
; DI float silu_f(float x) { return x * __builtin_amdgcn_rcpf(1.0f + __builtin_amdgcn_exp2f(-1.4426950408889634f * x)); }
; #define MFMA16(a, b, c) __builtin_amdgcn_mfma_f32_16x16x32_bf16((a), (b), (c), 0, 0, 0)
; DI void ssd_unit(LAS unsigned char* lds, const bf16* XBC, const float* DT, const bf16* PROJ, bf16* YG, int rb, int NC, int h, float A, float Dsk, const float* h0, float* hout, int tid) {
;     ...
;             const float x0 = bf_lo(gx[pt].x), x1 = bf_hi(gx[pt].x), x2 = bf_lo(gx[pt].y), x3 = bf_hi(gx[pt].y);
;             const float z0 = bf_lo(gz[pt].x), z1 = bf_hi(gz[pt].x), z2 = bf_lo(gz[pt].y), z3 = bf_hi(gz[pt].y);
;             u32x2 w; w.x = pkbf((y[0] + Dsk * x0) * silu_f(z0), (y[1] + Dsk * x1) * silu_f(z1)); w.y = pkbf((y[2] + Dsk * x2) * silu_f(z2), (y[3] + Dsk * x3) * silu_f(z3));
;             *(u32x2*)(YG + (size_t)(row0 + i) * 2048 + h * 64 + 16 * pb + 4 * quad) = w;
;         }
;         const float et = __expf(atot);
; #pragma unroll
;         for (int t = 0; t < 4; ++t) hacc[t] *= et;
; #pragma unroll
;         for (int s = 0; s < 2; ++s) {
;             const bf16x8 xf = tr_frag(T + XW, RSX, 32 * s, 16 * pbk, lane);
; #pragma unroll
;             for (int t = 0; t < 4; ++t) hacc[t] = MFMA16(tr_frag(T + BS, RSC, 32 * s, 16 * (nb0 + t), lane), xf, hacc[t]);
;         }
; #pragma unroll
;         for (int t = 0; t < 4; ++t) { u32x2 w; w.x = pkbf(hacc[t][0], hacc[t][1]); w.y = pkbf(hacc[t][2], hacc[t][3]);
;             *(LAS u32x2*)(Hn + (16 * pbk + l15) * RSC + (16 * (nb0 + t) + 4 * quad) * 2) = w; }
;         ac = acn; atot = atn;
;         __syncthreads();
.LBB0_1143:
	s_or_b64 exec, exec, s[0:1]
	v_add_u32_e32 v236, s62, v154
	v_add_u32_e32 v237, v97, v168
	v_add3_u32 v236, v236, v153, v167
	v_add_u32_e32 v238, v237, v93
	ds_read_b64_tr_b16 v[188:189], v236 offset:44032
	ds_read_b64_tr_b16 v[190:191], v236 offset:44608
	ds_read_b64_tr_b16 v[192:193], v238 offset:17408
	ds_read_b64_tr_b16 v[194:195], v238 offset:18496
	v_add_u32_e32 v238, v237, v138
	ds_read_b64_tr_b16 v[196:197], v238 offset:17408
	ds_read_b64_tr_b16 v[198:199], v238 offset:18496
	v_add_u32_e32 v238, v237, v139
	ds_read_b64_tr_b16 v[200:201], v238 offset:17408
	ds_read_b64_tr_b16 v[202:203], v238 offset:18496
	v_add_u32_e32 v238, v237, v140
	ds_read_b64_tr_b16 v[204:205], v238 offset:17408
	ds_read_b64_tr_b16 v[206:207], v238 offset:18496
	v_lshlrev_b32_e32 v54, 16, v126
	v_mul_f32_e32 v1, 0xbfb8aa3b, v54
	v_exp_f32_e32 v1, v1
	v_and_b32_e32 v55, 0xffff0000, v126
	v_lshlrev_b32_e32 v52, 16, v128
	v_and_b32_e32 v53, 0xffff0000, v128
	v_add_f32_e32 v1, 1.0, v1
	v_rcp_f32_e32 v56, v1
	v_mul_f32_e32 v1, 0xbfb8aa3b, v55
	v_exp_f32_e32 v1, v1
	v_pk_fma_f32 v[48:49], v[102:103], v[52:53], v[48:49]
	v_mov_b32_e32 v99, v3
	s_mulk_i32 s27, 0x4400
	v_add_f32_e32 v1, 1.0, v1
	v_rcp_f32_e32 v57, v1
	s_mov_b64 s[0:1], 0xf8000
	v_add_u32_e32 v106, 64, v106
	v_lshl_add_u64 v[112:113], v[112:113], 0, s[68:69]
	v_pk_mul_f32 v[52:53], v[56:57], v[54:55]
	v_lshlrev_b32_e32 v54, 16, v127
	v_mul_f32_e32 v1, 0xbfb8aa3b, v54
	v_exp_f32_e32 v1, v1
	v_and_b32_e32 v55, 0xffff0000, v127
	v_pk_mul_f32 v[48:49], v[52:53], v[48:49]
	v_lshlrev_b32_e32 v52, 16, v129
	v_add_f32_e32 v1, 1.0, v1
	v_rcp_f32_e32 v56, v1
	v_mul_f32_e32 v1, 0xbfb8aa3b, v55
	v_exp_f32_e32 v1, v1
	v_and_b32_e32 v53, 0xffff0000, v129
	v_pk_fma_f32 v[50:51], v[102:103], v[52:53], v[50:51]
	v_cvt_pk_bf16_f32 v48, v48, v49
	v_add_f32_e32 v1, 1.0, v1
	v_rcp_f32_e32 v57, v1
	v_mov_b32_e32 v1, 0x3fb8aa3b
	v_mul_f32_e32 v1, s11, v1
	v_lshl_add_u64 v[108:109], v[108:109], 0, s[30:31]
	v_pk_mul_f32 v[52:53], v[56:57], v[54:55]
	v_add_u32_e32 v239, v97, v169
	v_pk_mul_f32 v[50:51], v[52:53], v[50:51]
	v_add_u32_e32 v238, v239, v93
	v_cvt_pk_bf16_f32 v49, v50, v51
	v_lshl_add_u64 v[50:51], v[134:135], 0, v[98:99]
	global_store_dwordx2 v[50:51], v[48:49], off
	v_exp_f32_e32 v48, v1
	ds_read_b64_tr_b16 v[208:209], v236 offset:48640
	ds_read_b64_tr_b16 v[210:211], v236 offset:49216
	ds_read_b64_tr_b16 v[212:213], v238 offset:17408
	ds_read_b64_tr_b16 v[214:215], v238 offset:18496
	v_add_u32_e32 v238, v239, v138
	ds_read_b64_tr_b16 v[216:217], v238 offset:17408
	ds_read_b64_tr_b16 v[218:219], v238 offset:18496
	v_add_u32_e32 v238, v239, v139
	ds_read_b64_tr_b16 v[220:221], v238 offset:17408
	ds_read_b64_tr_b16 v[222:223], v238 offset:18496
	v_add_u32_e32 v238, v239, v140
	ds_read_b64_tr_b16 v[232:233], v238 offset:17408
	ds_read_b64_tr_b16 v[234:235], v238 offset:18496
	v_lshl_add_u64 v[110:111], v[110:111], 0, s[30:31]
	v_pk_mul_f32 v[10:11], v[10:11], v[48:49] op_sel_hi:[1,0]
	v_pk_mul_f32 v[8:9], v[8:9], v[48:49] op_sel_hi:[1,0]
	v_pk_mul_f32 v[14:15], v[14:15], v[48:49] op_sel_hi:[1,0]
	v_pk_mul_f32 v[12:13], v[12:13], v[48:49] op_sel_hi:[1,0]
	v_pk_mul_f32 v[18:19], v[18:19], v[48:49] op_sel_hi:[1,0]
	v_pk_mul_f32 v[16:17], v[16:17], v[48:49] op_sel_hi:[1,0]
	v_pk_mul_f32 v[34:35], v[34:35], v[48:49] op_sel_hi:[1,0]
	v_pk_mul_f32 v[32:33], v[32:33], v[48:49] op_sel_hi:[1,0]
	s_waitcnt lgkmcnt(15)
	v_mfma_f32_16x16x32_bf16 v[8:11], v[192:195], v[188:191], v[8:11]
	s_waitcnt lgkmcnt(14)
	v_mfma_f32_16x16x32_bf16 v[12:15], v[196:199], v[188:191], v[12:15]
	s_waitcnt lgkmcnt(12)
	v_mfma_f32_16x16x32_bf16 v[16:19], v[200:203], v[188:191], v[16:19]
	s_waitcnt lgkmcnt(10)
	v_mfma_f32_16x16x32_bf16 v[32:35], v[204:207], v[188:191], v[32:35]
	s_waitcnt lgkmcnt(6)
	v_mfma_f32_16x16x32_bf16 v[8:11], v[212:215], v[208:211], v[8:11]
	s_waitcnt lgkmcnt(4)
	v_mfma_f32_16x16x32_bf16 v[12:15], v[216:219], v[208:211], v[12:15]
	s_waitcnt lgkmcnt(2)
	v_mfma_f32_16x16x32_bf16 v[16:19], v[220:223], v[208:211], v[16:19]
	s_waitcnt lgkmcnt(0)
	v_mfma_f32_16x16x32_bf16 v[32:35], v[232:235], v[208:211], v[32:35]
	v_lshl_add_u64 v[116:117], v[116:117], 0, s[0:1]
	v_lshl_add_u64 v[104:105], v[104:105], 0, s[30:31]
	s_add_i32 s100, s63, 2
	s_cmp_lt_u32 s100, s9
	s_cbranch_scc1 .Lssd_wait_g8
	s_waitcnt vmcnt(2)
	s_branch .Lssd_wait_gdone
.Lssd_wait_g8:
	s_waitcnt vmcnt(8)
.Lssd_wait_gdone:
	s_cmp_lg_u32 s9, s10
	v_mov_b64_e32 v[128:129], v[120:121]
	v_add_u32_e32 v1, s27, v83
	v_mov_b64_e32 v[132:133], v[118:119]
	v_cvt_pk_bf16_f32 v48, v8, v9
	v_cvt_pk_bf16_f32 v49, v10, v11
	v_add_u32_e32 v50, v1, v93
	ds_write_b64 v50, v[48:49]
	v_cvt_pk_bf16_f32 v48, v12, v13
	v_cvt_pk_bf16_f32 v49, v14, v15
	v_add_u32_e32 v50, v1, v138
	ds_write_b64 v50, v[48:49]
	v_cvt_pk_bf16_f32 v48, v16, v17
	v_cvt_pk_bf16_f32 v49, v18, v19
	v_add_u32_e32 v50, v1, v139
	ds_write_b64 v50, v[48:49]
	v_cvt_pk_bf16_f32 v48, v32, v33
	v_cvt_pk_bf16_f32 v49, v34, v35
	v_add_u32_e32 v1, v1, v140
	v_mov_b64_e32 v[126:127], v[124:125]
	v_mov_b64_e32 v[130:131], v[122:123]
	s_mov_b32 s11, s26
	s_mov_b32 s63, s10
	ds_write_b64 v1, v[48:49]
	s_waitcnt lgkmcnt(0)
	s_barrier
	s_cbranch_scc0 .LBB0_1128

; DI void ssd_unit(LAS unsigned char* lds, const bf16* XBC, const float* DT, const bf16* PROJ, bf16* YG, int rb, int NC, int h, float A, float Dsk, const float* h0, float* hout, int tid) {
;     ...
;         if (c + 1 < NC) { SSD_STAGE(ts ^ 1, acn, atn); if (c + 2 < NC) SSD_LOAD(c + 2); }
.LBB0_1150:
	s_or_b64 exec, exec, s[26:27]
	s_xor_b32 s27, s64, 1
	v_add_u32_e32 v1, v151, v166
	s_andn2_b64 vcc, exec, s[0:1]
	ds_write_b64 v1, v[64:65]
	s_cbranch_vccnz .LBB0_1153
	s_waitcnt vmcnt(6)
	v_mul_f32_e64 v1, v101, -v95
	v_mov_b32_e32 v64, v3
	s_mul_i32 s0, s27, 0xd000
	s_add_i32 s0, s0, 0
	v_mov_b32_dpp v64, v1 row_shr:1 row_mask:0xf bank_mask:0xf
	v_fma_f32 v1, v101, -v95, v64
	v_mov_b32_e32 v64, v3
	v_lshlrev_b32_e32 v134, 16, v4
	v_add_f32_dpp v1, v1, v1 row_shr:2 row_mask:0xf bank_mask:0xf bound_ctrl:1
	v_and_b32_e32 v135, 0xffff0000, v4
	v_lshlrev_b32_e32 v172, 16, v5
	v_add_f32_dpp v1, v1, v1 row_shr:4 row_mask:0xf bank_mask:0xf bound_ctrl:1
	v_and_b32_e32 v173, 0xffff0000, v5
	v_lshlrev_b32_e32 v176, 16, v6
	v_add_f32_dpp v1, v1, v1 row_shr:8 row_mask:0xf bank_mask:0xf bound_ctrl:1
	v_and_b32_e32 v177, 0xffff0000, v6
	v_lshlrev_b32_e32 v180, 16, v7
	v_mov_b32_dpp v64, v1 row_bcast:15 row_mask:0xa bank_mask:0xf
	v_add_f32_e32 v1, v1, v64
	v_mov_b32_e32 v64, v3
	v_and_b32_e32 v181, 0xffff0000, v7
	s_nop 0
	v_mov_b32_dpp v64, v1 row_bcast:31 row_mask:0xc bank_mask:0xf
	v_add_f32_e32 v171, v1, v64
	ds_bpermute_b32 v1, v141, v171
	v_readlane_b32 s26, v171, 63
	ds_bpermute_b32 v64, v141, v101
	s_waitcnt lgkmcnt(0)
	v_pk_mul_f32 v[134:135], v[64:65], v[134:135] op_sel_hi:[0,1]
	v_sub_f32_e32 v1, s26, v1
	v_mul_f32_e32 v1, 0x3fb8aa3b, v1
	v_exp_f32_e32 v66, v1
	v_add3_u32 v1, s0, v142, v144
	v_pk_mul_f32 v[172:173], v[64:65], v[172:173] op_sel_hi:[0,1]
	v_pk_mul_f32 v[176:177], v[64:65], v[176:177] op_sel_hi:[0,1]
	v_pk_mul_f32 v[180:181], v[64:65], v[180:181] op_sel_hi:[0,1]
	ds_write_b128 v1, v[28:31]
	ds_write_b128 v1, v[36:39] offset:16
	ds_write_b128 v1, v[24:27] offset:17408
	ds_write_b128 v1, v[20:23] offset:17424
	v_pk_mul_f32 v[136:137], v[134:135], v[66:67] op_sel_hi:[1,0]
	v_pk_mul_f32 v[174:175], v[172:173], v[66:67] op_sel_hi:[1,0]
	v_pk_mul_f32 v[178:179], v[176:177], v[66:67] op_sel_hi:[1,0]
	v_pk_mul_f32 v[182:183], v[180:181], v[66:67] op_sel_hi:[1,0]
	v_cvt_pk_bf16_f32 v64, v134, v135
	v_cvt_pk_bf16_f32 v65, v172, v173
	v_cvt_pk_bf16_f32 v66, v176, v177
	v_cvt_pk_bf16_f32 v67, v180, v181
	v_add3_u32 v1, s0, v145, v80
	s_add_i32 s0, s63, 2
	ds_write_b128 v1, v[64:67] offset:34816
	v_cvt_pk_bf16_f32 v64, v136, v137
	v_cvt_pk_bf16_f32 v65, v174, v175
	v_cvt_pk_bf16_f32 v66, v178, v179
	v_cvt_pk_bf16_f32 v67, v182, v183
	s_cmp_ge_u32 s0, s9
	ds_write_b128 v1, v[64:67] offset:44032
	s_cbranch_scc1 .LBB0_1154
	v_lshl_add_u64 v[4:5], s[78:79], 0, v[108:109]
	v_lshl_add_u64 v[28:29], s[78:79], 0, v[110:111]
	global_load_dwordx4 v[4:7], v[4:5], off
	s_nop 0
	global_load_dwordx4 v[20:23], v[28:29], off offset:-2032
	global_load_dwordx4 v[24:27], v[28:29], off offset:-2048
	global_load_dwordx4 v[36:39], v[28:29], off offset:16
	s_nop 0
	global_load_dwordx4 v[28:31], v[28:29], off
	v_lshl_add_u64 v[64:65], s[78:79], 0, v[112:113]
	global_load_dword v101, v[64:65], off
	s_branch .LBB0_1154

;     ...
;     __syncthreads();
.LBB0_1169:
	s_waitcnt lgkmcnt(0)
	s_barrier

; template <class Epi, class Sched, bool ALIGN_EPI = false, bool SP2 = false>
; __device__ __forceinline__ void gemm_phase(PG8_LAS unsigned char* lds, const Gemm g, const Sched& S, const Epi& E) {
;     ...
;         const bool has_next = S.next(ui + 1, nxt);
;         const char* nA = has_next ? (const char*)g.A + (size_t)nxt.pm * tstep + (size_t)nxt.kt0 * kstep : cA; const char* nB = has_next ? (const char*)g.Bt + (size_t)nxt.pn * tstep + (size_t)nxt.kt0 * kstep : cB;
;     ...
; #pragma unroll
;         for (int a = 0; a < 2; ++a)
; #pragma unroll
;             for (int b = 0; b < 2; ++b)
; #pragma unroll
;                 for (int m = 0; m < 4; ++m)
; #pragma unroll
;                     for (int n = 0; n < 2; ++n) acc[a][b][m][n] = (f32x4){0.f, 0.f, 0.f, 0.f};
.LBB0_1623:
	s_ashr_i32 s49, s48, 31
	s_lshl_b64 s[50:51], s[48:49], 21
	s_add_u32 s47, s5, s50
	s_addc_u32 s49, s6, s51
	s_and_b64 s[50:51], s[40:41], exec
	s_cselect_b32 s51, s49, s1
	s_cselect_b32 s50, s47, s0
	s_ashr_i32 s47, s46, 31
	s_lshl_b64 s[52:53], s[46:47], 21
	s_add_u32 s47, s7, s52
	s_addc_u32 s49, s8, s53
	s_and_b64 s[52:53], s[40:41], exec
	s_cselect_b32 s53, s49, s27
	s_cselect_b32 s52, s47, s26
	s_add_u32 s56, s0, 0x100080
	s_addc_u32 s57, s1, 0
	s_add_u32 s47, s26, 0x100
	v_mov_b64_e32 v[4:5], 0
	s_addc_u32 s49, s27, 0
	s_mov_b32 s62, -2
	v_mov_b64_e32 v[6:7], 0
	v_mov_b64_e32 v[8:9], 0
	v_mov_b64_e32 v[10:11], 0
	v_mov_b64_e32 v[20:21], 0
	v_mov_b64_e32 v[22:23], 0
	v_mov_b64_e32 v[24:25], 0
	v_mov_b64_e32 v[26:27], 0
	v_mov_b64_e32 v[36:37], 0
	v_mov_b64_e32 v[38:39], 0
	v_mov_b64_e32 v[40:41], 0
	v_mov_b64_e32 v[42:43], 0
	v_mov_b64_e32 v[52:53], 0
	v_mov_b64_e32 v[54:55], 0
	v_mov_b64_e32 v[56:57], 0
	v_mov_b64_e32 v[58:59], 0
	v_mov_b64_e32 v[12:13], 0
	v_mov_b64_e32 v[14:15], 0
	v_mov_b64_e32 v[16:17], 0
	v_mov_b64_e32 v[18:19], 0
	v_mov_b64_e32 v[28:29], 0
	v_mov_b64_e32 v[30:31], 0
	v_mov_b64_e32 v[32:33], 0
	v_mov_b64_e32 v[34:35], 0
	v_mov_b64_e32 v[44:45], 0
	v_mov_b64_e32 v[46:47], 0
	v_mov_b64_e32 v[48:49], 0
	v_mov_b64_e32 v[50:51], 0
	v_mov_b64_e32 v[60:61], 0
	v_mov_b64_e32 v[62:63], 0
	v_mov_b64_e32 v[64:65], 0
	v_mov_b64_e32 v[66:67], 0
	v_mov_b64_e32 v[68:69], 0
	v_mov_b64_e32 v[70:71], 0
	v_mov_b64_e32 v[72:73], 0
	v_mov_b64_e32 v[74:75], 0
	v_mov_b64_e32 v[84:85], 0
	v_mov_b64_e32 v[86:87], 0
	v_mov_b64_e32 v[88:89], 0
	v_mov_b64_e32 v[90:91], 0
	v_mov_b64_e32 v[100:101], 0
	v_mov_b64_e32 v[102:103], 0
	v_mov_b64_e32 v[104:105], 0
	v_mov_b64_e32 v[106:107], 0
	v_mov_b64_e32 v[116:117], 0
	v_mov_b64_e32 v[118:119], 0
	v_mov_b64_e32 v[120:121], 0
	v_mov_b64_e32 v[122:123], 0
	v_mov_b64_e32 v[76:77], 0
	v_mov_b64_e32 v[78:79], 0
	v_mov_b64_e32 v[80:81], 0
	v_mov_b64_e32 v[82:83], 0
	v_mov_b64_e32 v[92:93], 0
	v_mov_b64_e32 v[94:95], 0
	v_mov_b64_e32 v[96:97], 0
	v_mov_b64_e32 v[98:99], 0
	v_mov_b64_e32 v[108:109], 0
	v_mov_b64_e32 v[110:111], 0
	v_mov_b64_e32 v[112:113], 0
	v_mov_b64_e32 v[114:115], 0
	v_mov_b64_e32 v[124:125], 0
	v_mov_b64_e32 v[126:127], 0
	v_mov_b64_e32 v[128:129], 0
	v_mov_b64_e32 v[130:131], 0
	v_add_u32_e32 v210, 0x10000, v147

; template <class Epi, class Sched, bool ALIGN_EPI = false, bool SP2 = false>
; __device__ __forceinline__ void gemm_phase(PG8_LAS unsigned char* lds, const Gemm g, const Sched& S, const Epi& E) {
;     ...
;         const bool has_next = S.next(ui + 1, nxt);
;         const char* nA = has_next ? (const char*)g.A + (size_t)nxt.pm * tstep + (size_t)nxt.kt0 * kstep : cA; const char* nB = has_next ? (const char*)g.Bt + (size_t)nxt.pn * tstep + (size_t)nxt.kt0 * kstep : cB;
;     ...
; #pragma unroll
;         for (int a = 0; a < 2; ++a)
; #pragma unroll
;             for (int b = 0; b < 2; ++b)
; #pragma unroll
;                 for (int m = 0; m < 4; ++m)
; #pragma unroll
;                     for (int n = 0; n < 2; ++n) acc[a][b][m][n] = (f32x4){0.f, 0.f, 0.f, 0.f};
.LBB0_2088:
	s_ashr_i32 s45, s44, 31
	s_lshl_b64 s[26:27], s[44:45], 21
	s_add_u32 s43, s5, s26
	s_addc_u32 s45, s6, s27
	s_and_b64 s[26:27], s[38:39], exec
	s_cselect_b32 s47, s45, s51
	s_cselect_b32 s46, s43, s50
	s_ashr_i32 s43, s42, 31
	s_lshl_b64 s[26:27], s[42:43], 21
	s_add_u32 s43, s7, s26
	s_addc_u32 s45, s8, s27
	s_and_b64 s[26:27], s[38:39], exec
	s_cselect_b32 s49, s45, s1
	s_cselect_b32 s48, s43, s0
	s_add_u32 s50, s50, 0x100080
	s_addc_u32 s51, s51, 0
	s_add_u32 s43, s0, 0x100
	v_mov_b64_e32 v[4:5], 0
	s_addc_u32 s45, s1, 0
	s_mov_b32 s60, -2
	v_mov_b64_e32 v[6:7], 0
	v_mov_b64_e32 v[8:9], 0
	v_mov_b64_e32 v[10:11], 0
	v_mov_b64_e32 v[20:21], 0
	v_mov_b64_e32 v[22:23], 0
	v_mov_b64_e32 v[24:25], 0
	v_mov_b64_e32 v[26:27], 0
	v_mov_b64_e32 v[36:37], 0
	v_mov_b64_e32 v[38:39], 0
	v_mov_b64_e32 v[40:41], 0
	v_mov_b64_e32 v[42:43], 0
	v_mov_b64_e32 v[52:53], 0
	v_mov_b64_e32 v[54:55], 0
	v_mov_b64_e32 v[56:57], 0
	v_mov_b64_e32 v[58:59], 0
	v_mov_b64_e32 v[12:13], 0
	v_mov_b64_e32 v[14:15], 0
	v_mov_b64_e32 v[16:17], 0
	v_mov_b64_e32 v[18:19], 0
	v_mov_b64_e32 v[28:29], 0
	v_mov_b64_e32 v[30:31], 0
	v_mov_b64_e32 v[32:33], 0
	v_mov_b64_e32 v[34:35], 0
	v_mov_b64_e32 v[44:45], 0
	v_mov_b64_e32 v[46:47], 0
	v_mov_b64_e32 v[48:49], 0
	v_mov_b64_e32 v[50:51], 0
	v_mov_b64_e32 v[60:61], 0
	v_mov_b64_e32 v[62:63], 0
	v_mov_b64_e32 v[64:65], 0
	v_mov_b64_e32 v[66:67], 0
	v_mov_b64_e32 v[68:69], 0
	v_mov_b64_e32 v[70:71], 0
	v_mov_b64_e32 v[72:73], 0
	v_mov_b64_e32 v[74:75], 0
	v_mov_b64_e32 v[84:85], 0
	v_mov_b64_e32 v[86:87], 0
	v_mov_b64_e32 v[88:89], 0
	v_mov_b64_e32 v[90:91], 0
	v_mov_b64_e32 v[100:101], 0
	v_mov_b64_e32 v[102:103], 0
	v_mov_b64_e32 v[104:105], 0
	v_mov_b64_e32 v[106:107], 0
	v_mov_b64_e32 v[116:117], 0
	v_mov_b64_e32 v[118:119], 0
	v_mov_b64_e32 v[120:121], 0
	v_mov_b64_e32 v[122:123], 0
	v_mov_b64_e32 v[76:77], 0
	v_mov_b64_e32 v[78:79], 0
	v_mov_b64_e32 v[80:81], 0
	v_mov_b64_e32 v[82:83], 0
	v_mov_b64_e32 v[92:93], 0
	v_mov_b64_e32 v[94:95], 0
	v_mov_b64_e32 v[96:97], 0
	v_mov_b64_e32 v[98:99], 0
	v_mov_b64_e32 v[108:109], 0
	v_mov_b64_e32 v[110:111], 0
	v_mov_b64_e32 v[112:113], 0
	v_mov_b64_e32 v[114:115], 0
	v_mov_b64_e32 v[124:125], 0
	v_mov_b64_e32 v[126:127], 0
	v_mov_b64_e32 v[128:129], 0
	v_mov_b64_e32 v[130:131], 0
	v_add_u32_e32 v210, 0x10000, v151

; template <class Epi, class Sched, bool ALIGN_EPI = false, bool SP2 = false>
; __device__ __forceinline__ void gemm_phase(PG8_LAS unsigned char* lds, const Gemm g, const Sched& S, const Epi& E) {
;     ...
;         const bool has_next = S.next(ui + 1, nxt);
;         const char* nA = has_next ? (const char*)g.A + (size_t)nxt.pm * tstep + (size_t)nxt.kt0 * kstep : cA; const char* nB = has_next ? (const char*)g.Bt + (size_t)nxt.pn * tstep + (size_t)nxt.kt0 * kstep : cB;
;     ...
; #pragma unroll
;         for (int a = 0; a < 2; ++a)
; #pragma unroll
;             for (int b = 0; b < 2; ++b)
; #pragma unroll
;                 for (int m = 0; m < 4; ++m)
; #pragma unroll
;                     for (int n = 0; n < 2; ++n) acc[a][b][m][n] = (f32x4){0.f, 0.f, 0.f, 0.f};
.LBB0_2114:
	s_ashr_i32 s49, s48, 31
	s_lshl_b64 s[26:27], s[48:49], 21
	s_add_u32 s50, s6, s26
	s_addc_u32 s51, s7, s27
	s_and_b64 s[26:27], s[44:45], exec
	s_cselect_b32 s49, s51, s1
	s_cselect_b32 s57, s50, s0
	s_ashr_i32 s47, s46, 31
	s_lshl_b64 s[26:27], s[46:47], 21
	s_add_u32 s52, s8, s26
	s_addc_u32 s53, s9, s27
	s_and_b64 s[26:27], s[44:45], exec
	s_cselect_b32 s47, s53, s59
	s_cselect_b32 s73, s52, s58
	s_add_u32 s40, s0, 0x100080
	s_addc_u32 s41, s1, 0
	s_add_u32 s58, s58, 0x100
	v_mov_b64_e32 v[4:5], 0
	s_addc_u32 s59, s59, 0
	s_mov_b32 s76, -2
	v_mov_b64_e32 v[6:7], 0
	v_mov_b64_e32 v[8:9], 0
	v_mov_b64_e32 v[10:11], 0
	v_mov_b64_e32 v[20:21], 0
	v_mov_b64_e32 v[22:23], 0
	v_mov_b64_e32 v[24:25], 0
	v_mov_b64_e32 v[26:27], 0
	v_mov_b64_e32 v[36:37], 0
	v_mov_b64_e32 v[38:39], 0
	v_mov_b64_e32 v[40:41], 0
	v_mov_b64_e32 v[42:43], 0
	v_mov_b64_e32 v[52:53], 0
	v_mov_b64_e32 v[54:55], 0
	v_mov_b64_e32 v[56:57], 0
	v_mov_b64_e32 v[58:59], 0
	v_mov_b64_e32 v[12:13], 0
	v_mov_b64_e32 v[14:15], 0
	v_mov_b64_e32 v[16:17], 0
	v_mov_b64_e32 v[18:19], 0
	v_mov_b64_e32 v[28:29], 0
	v_mov_b64_e32 v[30:31], 0
	v_mov_b64_e32 v[32:33], 0
	v_mov_b64_e32 v[34:35], 0
	v_mov_b64_e32 v[44:45], 0
	v_mov_b64_e32 v[46:47], 0
	v_mov_b64_e32 v[48:49], 0
	v_mov_b64_e32 v[50:51], 0
	v_mov_b64_e32 v[60:61], 0
	v_mov_b64_e32 v[62:63], 0
	v_mov_b64_e32 v[64:65], 0
	v_mov_b64_e32 v[66:67], 0
	v_mov_b64_e32 v[68:69], 0
	v_mov_b64_e32 v[70:71], 0
	v_mov_b64_e32 v[72:73], 0
	v_mov_b64_e32 v[74:75], 0
	v_mov_b64_e32 v[84:85], 0
	v_mov_b64_e32 v[86:87], 0
	v_mov_b64_e32 v[88:89], 0
	v_mov_b64_e32 v[90:91], 0
	v_mov_b64_e32 v[100:101], 0
	v_mov_b64_e32 v[102:103], 0
	v_mov_b64_e32 v[104:105], 0
	v_mov_b64_e32 v[106:107], 0
	v_mov_b64_e32 v[116:117], 0
	v_mov_b64_e32 v[118:119], 0
	v_mov_b64_e32 v[120:121], 0
	v_mov_b64_e32 v[122:123], 0
	v_mov_b64_e32 v[76:77], 0
	v_mov_b64_e32 v[78:79], 0
	v_mov_b64_e32 v[80:81], 0
	v_mov_b64_e32 v[82:83], 0
	v_mov_b64_e32 v[92:93], 0
	v_mov_b64_e32 v[94:95], 0
	v_mov_b64_e32 v[96:97], 0
	v_mov_b64_e32 v[98:99], 0
	v_mov_b64_e32 v[108:109], 0
	v_mov_b64_e32 v[110:111], 0
	v_mov_b64_e32 v[112:113], 0
	v_mov_b64_e32 v[114:115], 0
	v_mov_b64_e32 v[124:125], 0
	v_mov_b64_e32 v[126:127], 0
	v_mov_b64_e32 v[128:129], 0
	v_mov_b64_e32 v[130:131], 0
	v_add_u32_e32 v188, 0x10000, v191

; template <class Epi, class Sched, bool ALIGN_EPI = false, bool SP2 = false>
; __device__ __forceinline__ void gemm_phase(PG8_LAS unsigned char* lds, const Gemm g, const Sched& S, const Epi& E) {
;     ...
;         const bool has_next = S.next(ui + 1, nxt);
;         const char* nA = has_next ? (const char*)g.A + (size_t)nxt.pm * tstep + (size_t)nxt.kt0 * kstep : cA; const char* nB = has_next ? (const char*)g.Bt + (size_t)nxt.pn * tstep + (size_t)nxt.kt0 * kstep : cB;
;     ...
; #pragma unroll
;         for (int a = 0; a < 2; ++a)
; #pragma unroll
;             for (int b = 0; b < 2; ++b)
; #pragma unroll
;                 for (int m = 0; m < 4; ++m)
; #pragma unroll
;                     for (int n = 0; n < 2; ++n) acc[a][b][m][n] = (f32x4){0.f, 0.f, 0.f, 0.f};
.LBB0_2691:
	s_ashr_i32 s49, s48, 31
	s_lshl_b64 s[50:51], s[48:49], 18
	s_add_u32 s47, s5, s50
	s_addc_u32 s49, s6, s51
	s_and_b64 s[50:51], s[40:41], exec
	s_cselect_b32 s51, s49, s1
	s_cselect_b32 s50, s47, s0
	s_ashr_i32 s47, s46, 31
	s_lshl_b64 s[52:53], s[46:47], 18
	s_add_u32 s47, s7, s52
	s_addc_u32 s49, s8, s53
	s_and_b64 s[52:53], s[40:41], exec
	s_cselect_b32 s53, s49, s27
	s_cselect_b32 s52, s47, s26
	s_add_u32 s56, s0, 0x20080
	s_addc_u32 s57, s1, 0
	s_add_u32 s47, s26, 0x100
	v_mov_b64_e32 v[4:5], 0
	s_addc_u32 s49, s27, 0
	s_mov_b32 s62, -2
	v_mov_b64_e32 v[6:7], 0
	v_mov_b64_e32 v[8:9], 0
	v_mov_b64_e32 v[10:11], 0
	v_mov_b64_e32 v[20:21], 0
	v_mov_b64_e32 v[22:23], 0
	v_mov_b64_e32 v[24:25], 0
	v_mov_b64_e32 v[26:27], 0
	v_mov_b64_e32 v[36:37], 0
	v_mov_b64_e32 v[38:39], 0
	v_mov_b64_e32 v[40:41], 0
	v_mov_b64_e32 v[42:43], 0
	v_mov_b64_e32 v[52:53], 0
	v_mov_b64_e32 v[54:55], 0
	v_mov_b64_e32 v[56:57], 0
	v_mov_b64_e32 v[58:59], 0
	v_mov_b64_e32 v[12:13], 0
	v_mov_b64_e32 v[14:15], 0
	v_mov_b64_e32 v[16:17], 0
	v_mov_b64_e32 v[18:19], 0
	v_mov_b64_e32 v[28:29], 0
	v_mov_b64_e32 v[30:31], 0
	v_mov_b64_e32 v[32:33], 0
	v_mov_b64_e32 v[34:35], 0
	v_mov_b64_e32 v[44:45], 0
	v_mov_b64_e32 v[46:47], 0
	v_mov_b64_e32 v[48:49], 0
	v_mov_b64_e32 v[50:51], 0
	v_mov_b64_e32 v[60:61], 0
	v_mov_b64_e32 v[62:63], 0
	v_mov_b64_e32 v[64:65], 0
	v_mov_b64_e32 v[66:67], 0
	v_mov_b64_e32 v[68:69], 0
	v_mov_b64_e32 v[70:71], 0
	v_mov_b64_e32 v[72:73], 0
	v_mov_b64_e32 v[74:75], 0
	v_mov_b64_e32 v[84:85], 0
	v_mov_b64_e32 v[86:87], 0
	v_mov_b64_e32 v[88:89], 0
	v_mov_b64_e32 v[90:91], 0
	v_mov_b64_e32 v[100:101], 0
	v_mov_b64_e32 v[102:103], 0
	v_mov_b64_e32 v[104:105], 0
	v_mov_b64_e32 v[106:107], 0
	v_mov_b64_e32 v[116:117], 0
	v_mov_b64_e32 v[118:119], 0
	v_mov_b64_e32 v[120:121], 0
	v_mov_b64_e32 v[122:123], 0
	v_mov_b64_e32 v[76:77], 0
	v_mov_b64_e32 v[78:79], 0
	v_mov_b64_e32 v[80:81], 0
	v_mov_b64_e32 v[82:83], 0
	v_mov_b64_e32 v[92:93], 0
	v_mov_b64_e32 v[94:95], 0
	v_mov_b64_e32 v[96:97], 0
	v_mov_b64_e32 v[98:99], 0
	v_mov_b64_e32 v[108:109], 0
	v_mov_b64_e32 v[110:111], 0
	v_mov_b64_e32 v[112:113], 0
	v_mov_b64_e32 v[114:115], 0
	v_mov_b64_e32 v[124:125], 0
	v_mov_b64_e32 v[126:127], 0
	v_mov_b64_e32 v[128:129], 0
	v_mov_b64_e32 v[130:131], 0
	v_add_u32_e32 v210, 0x10000, v147

; template <class Epi, class Sched, bool ALIGN_EPI = false, bool SP2 = false>
; __device__ __forceinline__ void gemm_phase(PG8_LAS unsigned char* lds, const Gemm g, const Sched& S, const Epi& E) {
;     ...
;         const bool has_next = S.next(ui + 1, nxt);
;         const char* nA = has_next ? (const char*)g.A + (size_t)nxt.pm * tstep + (size_t)nxt.kt0 * kstep : cA; const char* nB = has_next ? (const char*)g.Bt + (size_t)nxt.pn * tstep + (size_t)nxt.kt0 * kstep : cB;
;     ...
; #pragma unroll
;         for (int a = 0; a < 2; ++a)
; #pragma unroll
;             for (int b = 0; b < 2; ++b)
; #pragma unroll
;                 for (int m = 0; m < 4; ++m)
; #pragma unroll
;                     for (int n = 0; n < 2; ++n) acc[a][b][m][n] = (f32x4){0.f, 0.f, 0.f, 0.f};
.LBB0_3158:
	s_ashr_i32 s51, s50, 31
	s_lshl_b64 s[26:27], s[50:51], 21
	s_add_u32 s36, s5, s26
	s_addc_u32 s37, s6, s27
	s_and_b64 s[26:27], s[38:39], exec
	s_cselect_b32 s51, s37, s25
	s_cselect_b32 s60, s36, s24
	s_ashr_i32 s49, s48, 31
	s_lshl_b64 s[26:27], s[48:49], 21
	s_add_u32 s52, s7, s26
	s_addc_u32 s53, s8, s27
	s_and_b64 s[26:27], s[38:39], exec
	s_cselect_b32 s49, s53, s1
	s_cselect_b32 s61, s52, s0
	s_add_u32 s24, s24, 0x100080
	s_addc_u32 s25, s25, 0
	s_add_u32 s62, s0, 0x100
	v_mov_b64_e32 v[4:5], 0
	s_addc_u32 s63, s1, 0
	s_mov_b32 s64, -2
	v_mov_b64_e32 v[6:7], 0
	v_mov_b64_e32 v[8:9], 0
	v_mov_b64_e32 v[10:11], 0
	v_mov_b64_e32 v[20:21], 0
	v_mov_b64_e32 v[22:23], 0
	v_mov_b64_e32 v[24:25], 0
	v_mov_b64_e32 v[26:27], 0
	v_mov_b64_e32 v[36:37], 0
	v_mov_b64_e32 v[38:39], 0
	v_mov_b64_e32 v[40:41], 0
	v_mov_b64_e32 v[42:43], 0
	v_mov_b64_e32 v[52:53], 0
	v_mov_b64_e32 v[54:55], 0
	v_mov_b64_e32 v[56:57], 0
	v_mov_b64_e32 v[58:59], 0
	v_mov_b64_e32 v[12:13], 0
	v_mov_b64_e32 v[14:15], 0
	v_mov_b64_e32 v[16:17], 0
	v_mov_b64_e32 v[18:19], 0
	v_mov_b64_e32 v[28:29], 0
	v_mov_b64_e32 v[30:31], 0
	v_mov_b64_e32 v[32:33], 0
	v_mov_b64_e32 v[34:35], 0
	v_mov_b64_e32 v[44:45], 0
	v_mov_b64_e32 v[46:47], 0
	v_mov_b64_e32 v[48:49], 0
	v_mov_b64_e32 v[50:51], 0
	v_mov_b64_e32 v[60:61], 0
	v_mov_b64_e32 v[62:63], 0
	v_mov_b64_e32 v[64:65], 0
	v_mov_b64_e32 v[66:67], 0
	v_mov_b64_e32 v[68:69], 0
	v_mov_b64_e32 v[70:71], 0
	v_mov_b64_e32 v[72:73], 0
	v_mov_b64_e32 v[74:75], 0
	v_mov_b64_e32 v[84:85], 0
	v_mov_b64_e32 v[86:87], 0
	v_mov_b64_e32 v[88:89], 0
	v_mov_b64_e32 v[90:91], 0
	v_mov_b64_e32 v[100:101], 0
	v_mov_b64_e32 v[102:103], 0
	v_mov_b64_e32 v[104:105], 0
	v_mov_b64_e32 v[106:107], 0
	v_mov_b64_e32 v[116:117], 0
	v_mov_b64_e32 v[118:119], 0
	v_mov_b64_e32 v[120:121], 0
	v_mov_b64_e32 v[122:123], 0
	v_mov_b64_e32 v[76:77], 0
	v_mov_b64_e32 v[78:79], 0
	v_mov_b64_e32 v[80:81], 0
	v_mov_b64_e32 v[82:83], 0
	v_mov_b64_e32 v[92:93], 0
	v_mov_b64_e32 v[94:95], 0
	v_mov_b64_e32 v[96:97], 0
	v_mov_b64_e32 v[98:99], 0
	v_mov_b64_e32 v[108:109], 0
	v_mov_b64_e32 v[110:111], 0
	v_mov_b64_e32 v[112:113], 0
	v_mov_b64_e32 v[114:115], 0
	v_mov_b64_e32 v[124:125], 0
	v_mov_b64_e32 v[126:127], 0
	v_mov_b64_e32 v[128:129], 0
	v_mov_b64_e32 v[130:131], 0
	v_add_u32_e32 v146, 0x10000, v149

; template <class Epi, class Sched, bool ALIGN_EPI = false, bool SP2 = false>
; __device__ __forceinline__ void gemm_phase(PG8_LAS unsigned char* lds, const Gemm g, const Sched& S, const Epi& E) {
;     ...
;         const bool has_next = S.next(ui + 1, nxt);
;         const char* nA = has_next ? (const char*)g.A + (size_t)nxt.pm * tstep + (size_t)nxt.kt0 * kstep : cA; const char* nB = has_next ? (const char*)g.Bt + (size_t)nxt.pn * tstep + (size_t)nxt.kt0 * kstep : cB;
;     ...
; #pragma unroll
;         for (int a = 0; a < 2; ++a)
; #pragma unroll
;             for (int b = 0; b < 2; ++b)
; #pragma unroll
;                 for (int m = 0; m < 4; ++m)
; #pragma unroll
;                     for (int n = 0; n < 2; ++n) acc[a][b][m][n] = (f32x4){0.f, 0.f, 0.f, 0.f};
.LBB0_3626:
	s_add_i32 s44, s46, -2
	s_add_u32 s45, s0, 0x100
	v_mov_b64_e32 v[4:5], 0
	s_addc_u32 s47, s1, 0
	s_mov_b32 s26, 0
	v_mov_b64_e32 v[6:7], 0
	v_mov_b64_e32 v[8:9], 0
	v_mov_b64_e32 v[10:11], 0
	v_mov_b64_e32 v[12:13], 0
	v_mov_b64_e32 v[14:15], 0
	v_mov_b64_e32 v[16:17], 0
	v_mov_b64_e32 v[18:19], 0
	v_mov_b64_e32 v[20:21], 0
	v_mov_b64_e32 v[22:23], 0
	v_mov_b64_e32 v[24:25], 0
	v_mov_b64_e32 v[26:27], 0
	v_mov_b64_e32 v[28:29], 0
	v_mov_b64_e32 v[30:31], 0
	v_mov_b64_e32 v[32:33], 0
	v_mov_b64_e32 v[34:35], 0
	v_mov_b64_e32 v[36:37], 0
	v_mov_b64_e32 v[38:39], 0
	v_mov_b64_e32 v[40:41], 0
	v_mov_b64_e32 v[42:43], 0
	v_mov_b64_e32 v[44:45], 0
	v_mov_b64_e32 v[46:47], 0
	v_mov_b64_e32 v[48:49], 0
	v_mov_b64_e32 v[50:51], 0
	v_mov_b64_e32 v[52:53], 0
	v_mov_b64_e32 v[54:55], 0
	v_mov_b64_e32 v[56:57], 0
	v_mov_b64_e32 v[58:59], 0
	v_mov_b64_e32 v[60:61], 0
	v_mov_b64_e32 v[62:63], 0
	v_mov_b64_e32 v[64:65], 0
	v_mov_b64_e32 v[66:67], 0
	v_mov_b64_e32 v[68:69], 0
	v_mov_b64_e32 v[70:71], 0
	v_mov_b64_e32 v[72:73], 0
	v_mov_b64_e32 v[74:75], 0
	v_mov_b64_e32 v[76:77], 0
	v_mov_b64_e32 v[78:79], 0
	v_mov_b64_e32 v[80:81], 0
	v_mov_b64_e32 v[82:83], 0
	v_mov_b64_e32 v[84:85], 0
	v_mov_b64_e32 v[86:87], 0
	v_mov_b64_e32 v[88:89], 0
	v_mov_b64_e32 v[90:91], 0
	v_mov_b64_e32 v[92:93], 0
	v_mov_b64_e32 v[94:95], 0
	v_mov_b64_e32 v[96:97], 0
	v_mov_b64_e32 v[98:99], 0
	v_mov_b64_e32 v[100:101], 0
	v_mov_b64_e32 v[102:103], 0
	v_mov_b64_e32 v[104:105], 0
	v_mov_b64_e32 v[106:107], 0
	v_mov_b64_e32 v[108:109], 0
	v_mov_b64_e32 v[110:111], 0
	v_mov_b64_e32 v[112:113], 0
	v_mov_b64_e32 v[114:115], 0
	v_mov_b64_e32 v[116:117], 0
	v_mov_b64_e32 v[118:119], 0
	v_mov_b64_e32 v[120:121], 0
	v_mov_b64_e32 v[122:123], 0
	v_mov_b64_e32 v[124:125], 0
	v_mov_b64_e32 v[126:127], 0
	v_mov_b64_e32 v[128:129], 0
	v_mov_b64_e32 v[130:131], 0
	v_add_u32_e32 v162, 0x10000, v166
